# Q|K and V^T epilogues: their bias / sum-of-squares loads were issued one at a time with a wait after each (12 and 16 round trips per tile); now issued together
# speedup vs baseline: 1.0063x; 1.0063x over previous
;     __device__ __forceinline__ void operator()(const Acc& acc, const Unit& u, int wr, int wc, int fr, int fq) const {
;     ...
;         const float bs = (u.pn < nscale_tiles) ? bscale : 1.f;
;         f32x4 bv[2][2];
; #pragma unroll
;         for (int bj = 0; bj < 2; ++bj)
; #pragma unroll
;             for (int n = 0; n < 2; ++n) bv[bj][n] = bias ? *(const f32x4*)(bias + col0 + bj * HALF + 4 * n) * bs : (f32x4){0.f, 0.f, 0.f, 0.f};
;         ssq_t rrv[8];
; #pragma unroll
;         for (int q = 0; q < 8; ++q) rrv[q] = ssq ? ssq[row0 + (q >> 2) * HALF + (q & 3) * 16] : 0u;
.LBB0_307:
	s_cmp_lt_i32 s1, 8
	v_lshl_or_b32 v154, s1, 8, v163
	s_cselect_b64 vcc, -1, 0
	v_cndmask_b32_e32 v156, 1.0, v205, vcc
	v_ashrrev_i32_e32 v155, 31, v154
	v_cndmask_b32_e64 v139, 0, 1, s[30:31]
	v_mov_b32_e32 v157, v156
	v_lshl_add_u64 v[158:159], v[154:155], 2, s[24:25]
	v_mov_b32_e32 v138, 0
	v_cmp_ne_u32_e64 s[2:3], 1, v139
	s_andn2_b64 vcc, exec, s[30:31]
	v_mov_b32_e32 v140, 0
	v_mov_b32_e32 v141, 0
	v_mov_b32_e32 v142, 0
	v_mov_b32_e32 v143, 0
	s_mov_b32 s69, 0x14000
	s_mov_b32 s39, 0x1c000
	s_mov_b32 s38, 0x20000
	s_mov_b32 s68, 0xb0000
	s_mov_b32 s62, 0x48000
	s_mov_b32 s63, 0x4c000
	global_load_dwordx4 v[178:181], v[158:159], off
	global_load_dwordx4 v[182:185], v[158:159], off offset:16
	global_load_dwordx4 v[186:189], v[158:159], off offset:512
	global_load_dwordx4 v[190:193], v[158:159], off offset:528
	v_lshl_add_u32 v216, s0, 8, v161
	v_ashrrev_i32_e32 v217, 31, v216
	v_lshl_add_u64 v[216:217], v[216:217], 2, s[26:27]
	global_load_dword v208, v[216:217], off
	global_load_dword v209, v[216:217], off offset:64
	global_load_dword v210, v[216:217], off offset:128
	global_load_dword v211, v[216:217], off offset:192
	global_load_dword v212, v[216:217], off offset:512
	global_load_dword v213, v[216:217], off offset:576
	global_load_dword v214, v[216:217], off offset:640
	global_load_dword v215, v[216:217], off offset:704
	s_cbranch_vccnz .LBB0_309
	v_mov_b32_e32 v144, v156
	v_mov_b32_e32 v145, v156
	s_waitcnt vmcnt(0)
	v_mov_b64_e32 v[140:141], v[178:179]
	v_mov_b64_e32 v[142:143], v[180:181]
	v_pk_mul_f32 v[142:143], v[144:145], v[142:143]
	v_pk_mul_f32 v[140:141], v[156:157], v[140:141]
.LBB0_309:
	s_and_b64 vcc, exec, s[2:3]
	v_mov_b32_e32 v139, 0
	v_mov_b32_e32 v146, 0
	v_mov_b32_e32 v147, 0
	s_cbranch_vccnz .LBB0_311
	v_mov_b32_e32 v138, v156
	v_mov_b32_e32 v139, v156
	s_waitcnt vmcnt(0)
	v_mov_b64_e32 v[144:145], v[182:183]
	v_mov_b64_e32 v[146:147], v[184:185]
	v_pk_mul_f32 v[146:147], v[138:139], v[146:147]
	v_pk_mul_f32 v[138:139], v[156:157], v[144:145]
.LBB0_311:
	v_mov_b32_e32 v144, 0
	s_and_b64 vcc, exec, s[2:3]
	v_mov_b32_e32 v148, 0
	v_mov_b32_e32 v149, 0
	v_mov_b32_e32 v150, 0
	v_mov_b32_e32 v151, 0
	s_cbranch_vccnz .LBB0_313
	v_mov_b32_e32 v152, v156
	v_mov_b32_e32 v153, v156
	s_waitcnt vmcnt(0)
	v_mov_b64_e32 v[148:149], v[186:187]
	v_mov_b64_e32 v[150:151], v[188:189]
	v_pk_mul_f32 v[150:151], v[152:153], v[150:151]
	v_pk_mul_f32 v[148:149], v[156:157], v[148:149]
.LBB0_313:
	s_and_b64 vcc, exec, s[2:3]
	v_mov_b32_e32 v145, 0
	v_mov_b32_e32 v152, 0
	v_mov_b32_e32 v153, 0
	s_cbranch_vccnz .LBB0_315
	v_mov_b32_e32 v144, v156
	v_mov_b32_e32 v145, v156
	s_waitcnt vmcnt(0)
	v_mov_b64_e32 v[166:167], v[190:191]
	v_mov_b64_e32 v[168:169], v[192:193]
	v_pk_mul_f32 v[152:153], v[144:145], v[168:169]
	v_pk_mul_f32 v[144:145], v[156:157], v[166:167]
.LBB0_315:
	v_lshl_add_u32 v156, s0, 8, v161
	v_cndmask_b32_e64 v157, 0, 1, s[34:35]
	v_mov_b32_e32 v170, 0
	v_cmp_ne_u32_e64 s[2:3], 1, v157
	s_andn2_b64 vcc, exec, s[34:35]
	v_ashrrev_i32_e32 v157, 31, v156
	v_mov_b32_e32 v171, 0
	s_cbranch_vccnz .LBB0_317
	v_lshl_add_u64 v[158:159], v[156:157], 2, s[26:27]
	s_waitcnt vmcnt(0)
	v_cvt_f32_u32_e32 v171, v208
.LBB0_317:
	s_and_b64 vcc, exec, s[2:3]
	s_cbranch_vccnz .LBB0_319
	v_lshl_add_u64 v[158:159], v[156:157], 2, s[26:27]
	s_waitcnt vmcnt(0)
	v_cvt_f32_u32_e32 v170, v209
.LBB0_319:
	v_mov_b32_e32 v168, 0
	s_and_b64 vcc, exec, s[2:3]
	v_mov_b32_e32 v169, 0
	s_cbranch_vccnz .LBB0_321
	v_lshl_add_u64 v[158:159], v[156:157], 2, s[26:27]
	s_waitcnt vmcnt(0)
	v_cvt_f32_u32_e32 v169, v210
.LBB0_321:
	s_and_b64 vcc, exec, s[2:3]
	s_cbranch_vccnz .LBB0_323
	v_lshl_add_u64 v[158:159], v[156:157], 2, s[26:27]
	s_waitcnt vmcnt(0)
	v_cvt_f32_u32_e32 v168, v211
.LBB0_323:
	v_mov_b32_e32 v166, 0
	s_and_b64 vcc, exec, s[2:3]
	v_mov_b32_e32 v167, 0
	s_cbranch_vccnz .LBB0_325
	v_lshl_add_u64 v[158:159], v[156:157], 2, s[26:27]
	s_waitcnt vmcnt(0)
	v_cvt_f32_u32_e32 v167, v212
.LBB0_325:
	s_and_b64 vcc, exec, s[2:3]
	s_cbranch_vccnz .LBB0_327
	v_lshl_add_u64 v[158:159], v[156:157], 2, s[26:27]
	s_waitcnt vmcnt(0)
	v_cvt_f32_u32_e32 v166, v213
.LBB0_327:
	v_mov_b32_e32 v159, 0
	s_and_b64 vcc, exec, s[2:3]
	v_mov_b32_e32 v165, 0
	s_cbranch_vccnz .LBB0_329
	v_lshl_add_u64 v[172:173], v[156:157], 2, s[26:27]
	s_waitcnt vmcnt(0)
	v_cvt_f32_u32_e32 v165, v214
.LBB0_329:
	s_and_b64 vcc, exec, s[2:3]
	s_cbranch_vccnz .LBB0_331
	v_lshl_add_u64 v[158:159], v[156:157], 2, s[26:27]
	s_waitcnt vmcnt(0)
	v_cvt_f32_u32_e32 v159, v215

;     __device__ __forceinline__ void operator()(const Acc& acc, const Unit& u, int wr, int wc, int fr, int fq) const {
;     ...
;             for (int n = 0; n < 2; ++n) { const ssq_t* s = ssq + col0 + bj * HALF + 4 * n; rv[bj][n] = (f32x4){rms_r(s[0]), rms_r(s[1]), rms_r(s[2]), rms_r(s[3])}; }
.LBB0_361:
	v_lshl_or_b32 v142, s1, 8, v165
	v_ashrrev_i32_e32 v143, 31, v142
	v_lshl_add_u64 v[146:147], v[142:143], 2, s[14:15]
	global_load_dword v180, v[146:147], off
	global_load_dword v181, v[146:147], off offset:4
	global_load_dword v182, v[146:147], off offset:8
	global_load_dword v183, v[146:147], off offset:12
	global_load_dword v184, v[146:147], off offset:16
	global_load_dword v185, v[146:147], off offset:20
	global_load_dword v186, v[146:147], off offset:24
	global_load_dword v187, v[146:147], off offset:28
	global_load_dword v188, v[146:147], off offset:512
	global_load_dword v189, v[146:147], off offset:516
	global_load_dword v190, v[146:147], off offset:520
	global_load_dword v191, v[146:147], off offset:524
	global_load_dword v192, v[146:147], off offset:528
	global_load_dword v193, v[146:147], off offset:532
	v_mov_b32_e32 v139, 0x358637bd
	v_lshlrev_b64 v[178:179], 1, v[142:143]
	s_mov_b32 s69, 0x14000
	s_mov_b32 s35, 0x30000
	s_mov_b32 s68, 0xb0000
	s_mov_b32 s34, 0x40000
	s_mov_b32 s58, 0x34000
	s_mov_b32 s59, 0x38000
	s_mov_b32 s60, 0x3c000
	s_mov_b32 s61, 0x44000
	s_mov_b32 s62, 0x48000
	s_mov_b32 s63, 0x4c000
	s_waitcnt vmcnt(0)
	v_cvt_f32_u32_e32 v138, v180
	v_fmac_f32_e32 v139, 0x36800000, v138
	v_cmp_gt_f32_e32 vcc, s66, v139
	v_mul_f32_e32 v138, 0x4f800000, v139
	s_nop 0
	v_cndmask_b32_e32 v138, v139, v138, vcc
	v_sqrt_f32_e32 v139, v138
	s_nop 0
	v_add_u32_e32 v140, -1, v139
	v_fma_f32 v141, -v140, v139, v138
	v_cmp_ge_f32_e64 s[2:3], 0, v141
	v_add_u32_e32 v141, 1, v139
	s_nop 0
	v_cndmask_b32_e64 v140, v139, v140, s[2:3]
	v_fma_f32 v139, -v141, v139, v138
	v_cmp_lt_f32_e64 s[2:3], 0, v139
	s_nop 1
	v_cndmask_b32_e64 v139, v140, v141, s[2:3]
	v_mul_f32_e32 v140, 0x37800000, v139
	v_cndmask_b32_e32 v139, v139, v140, vcc
	v_cmp_class_f32_e32 vcc, v138, v196
	s_nop 1
	v_cndmask_b32_e32 v138, v139, v138, vcc
	v_div_scale_f32 v139, s[2:3], v138, v138, 1.0
	v_rcp_f32_e32 v140, v139
	s_nop 0
	v_fma_f32 v141, -v139, v140, 1.0
	v_fmac_f32_e32 v140, v141, v140
	v_div_scale_f32 v141, vcc, 1.0, v138, 1.0
	v_mul_f32_e32 v144, v141, v140
	v_fma_f32 v145, -v139, v144, v141
	v_fmac_f32_e32 v144, v145, v140
	v_fma_f32 v139, -v139, v144, v141
	v_div_fmas_f32 v139, v139, v140, v144
	v_div_fixup_f32 v138, v139, v138, 1.0
	v_mov_b32_e32 v140, 0x358637bd
	s_waitcnt vmcnt(0)
	v_cvt_f32_u32_e32 v139, v181
	v_fmac_f32_e32 v140, 0x36800000, v139
	v_cmp_gt_f32_e32 vcc, s66, v140
	v_mul_f32_e32 v139, 0x4f800000, v140
	s_nop 0
	v_cndmask_b32_e32 v139, v140, v139, vcc
	v_sqrt_f32_e32 v140, v139
	s_nop 0
	v_add_u32_e32 v141, -1, v140
	v_fma_f32 v144, -v141, v140, v139
	v_cmp_ge_f32_e64 s[2:3], 0, v144
	v_add_u32_e32 v144, 1, v140
	s_nop 0
	v_cndmask_b32_e64 v141, v140, v141, s[2:3]
	v_fma_f32 v140, -v144, v140, v139
	v_cmp_lt_f32_e64 s[2:3], 0, v140
	s_nop 1
	v_cndmask_b32_e64 v140, v141, v144, s[2:3]
	v_mul_f32_e32 v141, 0x37800000, v140
	v_cndmask_b32_e32 v140, v140, v141, vcc
	v_cmp_class_f32_e32 vcc, v139, v196
	s_nop 1
	v_cndmask_b32_e32 v139, v140, v139, vcc
	v_div_scale_f32 v140, s[2:3], v139, v139, 1.0
	v_rcp_f32_e32 v141, v140
	s_nop 0
	v_fma_f32 v144, -v140, v141, 1.0
	v_fmac_f32_e32 v141, v144, v141
	v_div_scale_f32 v144, vcc, 1.0, v139, 1.0
	v_mul_f32_e32 v145, v144, v141
	v_fma_f32 v148, -v140, v145, v144
	v_fmac_f32_e32 v145, v148, v141
	v_fma_f32 v140, -v140, v145, v144
	v_div_fmas_f32 v140, v140, v141, v145
	v_div_fixup_f32 v139, v140, v139, 1.0
	v_mov_b32_e32 v141, 0x358637bd
	s_waitcnt vmcnt(0)
	v_cvt_f32_u32_e32 v140, v182
	v_fmac_f32_e32 v141, 0x36800000, v140
	v_cmp_gt_f32_e32 vcc, s66, v141
	v_mul_f32_e32 v140, 0x4f800000, v141
	s_nop 0
	v_cndmask_b32_e32 v140, v141, v140, vcc
	v_sqrt_f32_e32 v141, v140
	s_nop 0
	v_add_u32_e32 v144, -1, v141
	v_fma_f32 v145, -v144, v141, v140
	v_cmp_ge_f32_e64 s[2:3], 0, v145
	v_add_u32_e32 v145, 1, v141
	s_nop 0
	v_cndmask_b32_e64 v144, v141, v144, s[2:3]
	v_fma_f32 v141, -v145, v141, v140
	v_cmp_lt_f32_e64 s[2:3], 0, v141
	s_nop 1
	v_cndmask_b32_e64 v141, v144, v145, s[2:3]
	v_mul_f32_e32 v144, 0x37800000, v141
	v_cndmask_b32_e32 v141, v141, v144, vcc
	v_cmp_class_f32_e32 vcc, v140, v196
	s_nop 1
	v_cndmask_b32_e32 v140, v141, v140, vcc
	v_div_scale_f32 v141, s[2:3], v140, v140, 1.0
	v_rcp_f32_e32 v144, v141
	s_nop 0
	v_fma_f32 v145, -v141, v144, 1.0
	v_fmac_f32_e32 v144, v145, v144
	v_div_scale_f32 v145, vcc, 1.0, v140, 1.0
	v_mul_f32_e32 v148, v145, v144
	v_fma_f32 v149, -v141, v148, v145
	v_fmac_f32_e32 v148, v149, v144
	v_fma_f32 v141, -v141, v148, v145
	v_div_fmas_f32 v141, v141, v144, v148
	v_div_fixup_f32 v140, v141, v140, 1.0
	v_mov_b32_e32 v144, 0x358637bd
	s_waitcnt vmcnt(0)
	v_cvt_f32_u32_e32 v141, v183
	v_fmac_f32_e32 v144, 0x36800000, v141
	v_cmp_gt_f32_e32 vcc, s66, v144
	v_mul_f32_e32 v141, 0x4f800000, v144
	s_nop 0
	v_cndmask_b32_e32 v141, v144, v141, vcc
	v_sqrt_f32_e32 v144, v141
	s_nop 0
	v_add_u32_e32 v145, -1, v144
	v_fma_f32 v148, -v145, v144, v141
	v_cmp_ge_f32_e64 s[2:3], 0, v148
	v_add_u32_e32 v148, 1, v144
	s_nop 0
	v_cndmask_b32_e64 v145, v144, v145, s[2:3]
	v_fma_f32 v144, -v148, v144, v141
	v_cmp_lt_f32_e64 s[2:3], 0, v144
	s_nop 1
	v_cndmask_b32_e64 v144, v145, v148, s[2:3]
	v_mul_f32_e32 v145, 0x37800000, v144
	v_cndmask_b32_e32 v144, v144, v145, vcc
	v_cmp_class_f32_e32 vcc, v141, v196
	s_nop 1
	v_cndmask_b32_e32 v141, v144, v141, vcc
	v_div_scale_f32 v144, s[2:3], v141, v141, 1.0
	v_rcp_f32_e32 v145, v144
	s_nop 0
	v_fma_f32 v148, -v144, v145, 1.0
	v_fmac_f32_e32 v145, v148, v145
	v_div_scale_f32 v148, vcc, 1.0, v141, 1.0
	v_mul_f32_e32 v149, v148, v145
	v_fma_f32 v150, -v144, v149, v148
	v_fmac_f32_e32 v149, v150, v145
	v_fma_f32 v144, -v144, v149, v148
	v_div_fmas_f32 v144, v144, v145, v149
	v_div_fixup_f32 v141, v144, v141, 1.0
	v_mov_b32_e32 v145, 0x358637bd
	s_waitcnt vmcnt(0)
;     __device__ __forceinline__ void operator()(const Acc& acc, const Unit& u, int wr, int wc, int fr, int fq) const {
;     ...
;             for (int n = 0; n < 2; ++n) { const ssq_t* s = ssq + col0 + bj * HALF + 4 * n; rv[bj][n] = (f32x4){rms_r(s[0]), rms_r(s[1]), rms_r(s[2]), rms_r(s[3])}; }
	v_cvt_f32_u32_e32 v144, v184
	v_fmac_f32_e32 v145, 0x36800000, v144
	v_cmp_gt_f32_e32 vcc, s66, v145
	v_mul_f32_e32 v144, 0x4f800000, v145
	s_nop 0
	v_cndmask_b32_e32 v144, v145, v144, vcc
	v_sqrt_f32_e32 v145, v144
	s_nop 0
	v_add_u32_e32 v148, -1, v145
	v_fma_f32 v149, -v148, v145, v144
	v_cmp_ge_f32_e64 s[2:3], 0, v149
	v_add_u32_e32 v149, 1, v145
	s_nop 0
	v_cndmask_b32_e64 v148, v145, v148, s[2:3]
	v_fma_f32 v145, -v149, v145, v144
	v_cmp_lt_f32_e64 s[2:3], 0, v145
	s_nop 1
	v_cndmask_b32_e64 v145, v148, v149, s[2:3]
	v_mul_f32_e32 v148, 0x37800000, v145
	v_cndmask_b32_e32 v145, v145, v148, vcc
	v_cmp_class_f32_e32 vcc, v144, v196
	s_nop 1
	v_cndmask_b32_e32 v144, v145, v144, vcc
	v_div_scale_f32 v145, s[2:3], v144, v144, 1.0
	v_rcp_f32_e32 v148, v145
	s_nop 0
	v_fma_f32 v149, -v145, v148, 1.0
	v_fmac_f32_e32 v148, v149, v148
	v_div_scale_f32 v149, vcc, 1.0, v144, 1.0
	v_mul_f32_e32 v150, v149, v148
	v_fma_f32 v151, -v145, v150, v149
	v_fmac_f32_e32 v150, v151, v148
	v_fma_f32 v145, -v145, v150, v149
	v_div_fmas_f32 v145, v145, v148, v150
	v_div_fixup_f32 v144, v145, v144, 1.0
	v_mov_b32_e32 v148, 0x358637bd
	s_waitcnt vmcnt(0)
	v_cvt_f32_u32_e32 v145, v185
	v_fmac_f32_e32 v148, 0x36800000, v145
	v_cmp_gt_f32_e32 vcc, s66, v148
	v_mul_f32_e32 v145, 0x4f800000, v148
	s_nop 0
	v_cndmask_b32_e32 v145, v148, v145, vcc
	v_sqrt_f32_e32 v148, v145
	s_nop 0
	v_add_u32_e32 v149, -1, v148
	v_fma_f32 v150, -v149, v148, v145
	v_cmp_ge_f32_e64 s[2:3], 0, v150
	v_add_u32_e32 v150, 1, v148
	s_nop 0
	v_cndmask_b32_e64 v149, v148, v149, s[2:3]
	v_fma_f32 v148, -v150, v148, v145
	v_cmp_lt_f32_e64 s[2:3], 0, v148
	s_nop 1
	v_cndmask_b32_e64 v148, v149, v150, s[2:3]
	v_mul_f32_e32 v149, 0x37800000, v148
	v_cndmask_b32_e32 v148, v148, v149, vcc
	v_cmp_class_f32_e32 vcc, v145, v196
	s_nop 1
	v_cndmask_b32_e32 v145, v148, v145, vcc
	v_div_scale_f32 v148, s[2:3], v145, v145, 1.0
	v_rcp_f32_e32 v149, v148
	s_nop 0
	v_fma_f32 v150, -v148, v149, 1.0
	v_fmac_f32_e32 v149, v150, v149
	v_div_scale_f32 v150, vcc, 1.0, v145, 1.0
	v_mul_f32_e32 v151, v150, v149
	v_fma_f32 v152, -v148, v151, v150
	v_fmac_f32_e32 v151, v152, v149
	v_fma_f32 v148, -v148, v151, v150
	v_div_fmas_f32 v148, v148, v149, v151
	v_div_fixup_f32 v145, v148, v145, 1.0
	v_mov_b32_e32 v149, 0x358637bd
	s_waitcnt vmcnt(0)
	v_cvt_f32_u32_e32 v148, v186
	v_fmac_f32_e32 v149, 0x36800000, v148
	v_cmp_gt_f32_e32 vcc, s66, v149
	v_mul_f32_e32 v148, 0x4f800000, v149
	s_nop 0
	v_cndmask_b32_e32 v148, v149, v148, vcc
	v_sqrt_f32_e32 v149, v148
	s_nop 0
	v_add_u32_e32 v150, -1, v149
	v_fma_f32 v151, -v150, v149, v148
	v_cmp_ge_f32_e64 s[2:3], 0, v151
	v_add_u32_e32 v151, 1, v149
	s_nop 0
	v_cndmask_b32_e64 v150, v149, v150, s[2:3]
	v_fma_f32 v149, -v151, v149, v148
	v_cmp_lt_f32_e64 s[2:3], 0, v149
	s_nop 1
	v_cndmask_b32_e64 v149, v150, v151, s[2:3]
	v_mul_f32_e32 v150, 0x37800000, v149
	v_cndmask_b32_e32 v149, v149, v150, vcc
	v_cmp_class_f32_e32 vcc, v148, v196
	s_nop 1
	v_cndmask_b32_e32 v148, v149, v148, vcc
	v_div_scale_f32 v149, s[2:3], v148, v148, 1.0
	v_rcp_f32_e32 v150, v149
	s_nop 0
	v_fma_f32 v151, -v149, v150, 1.0
	v_fmac_f32_e32 v150, v151, v150
	v_div_scale_f32 v151, vcc, 1.0, v148, 1.0
	v_mul_f32_e32 v152, v151, v150
	v_fma_f32 v153, -v149, v152, v151
	v_fmac_f32_e32 v152, v153, v150
	v_fma_f32 v149, -v149, v152, v151
	v_div_fmas_f32 v149, v149, v150, v152
	v_div_fixup_f32 v148, v149, v148, 1.0
	v_mov_b32_e32 v150, 0x358637bd
	s_waitcnt vmcnt(0)
	v_cvt_f32_u32_e32 v149, v187
	v_fmac_f32_e32 v150, 0x36800000, v149
	v_cmp_gt_f32_e32 vcc, s66, v150
	v_mul_f32_e32 v149, 0x4f800000, v150
	s_nop 0
	v_cndmask_b32_e32 v149, v150, v149, vcc
	v_sqrt_f32_e32 v150, v149
	s_nop 0
	v_add_u32_e32 v151, -1, v150
	v_fma_f32 v152, -v151, v150, v149
	v_cmp_ge_f32_e64 s[2:3], 0, v152
	v_add_u32_e32 v152, 1, v150
	s_nop 0
	v_cndmask_b32_e64 v151, v150, v151, s[2:3]
	v_fma_f32 v150, -v152, v150, v149
	v_cmp_lt_f32_e64 s[2:3], 0, v150
	s_nop 1
	v_cndmask_b32_e64 v150, v151, v152, s[2:3]
	v_mul_f32_e32 v151, 0x37800000, v150
	v_cndmask_b32_e32 v150, v150, v151, vcc
	v_cmp_class_f32_e32 vcc, v149, v196
	s_nop 1
	v_cndmask_b32_e32 v149, v150, v149, vcc
	v_div_scale_f32 v150, s[2:3], v149, v149, 1.0
	v_rcp_f32_e32 v151, v150
	s_nop 0
	v_fma_f32 v152, -v150, v151, 1.0
	v_fmac_f32_e32 v151, v152, v151
	v_div_scale_f32 v152, vcc, 1.0, v149, 1.0
	v_mul_f32_e32 v153, v152, v151
	v_fma_f32 v154, -v150, v153, v152
	v_fmac_f32_e32 v153, v154, v151
	v_fma_f32 v150, -v150, v153, v152
	v_div_fmas_f32 v150, v150, v151, v153
	v_div_fixup_f32 v149, v150, v149, 1.0
	v_mov_b32_e32 v151, 0x358637bd
	s_waitcnt vmcnt(0)
	v_cvt_f32_u32_e32 v150, v188
	v_fmac_f32_e32 v151, 0x36800000, v150
	v_cmp_gt_f32_e32 vcc, s66, v151
	v_mul_f32_e32 v150, 0x4f800000, v151
	s_nop 0
	v_cndmask_b32_e32 v150, v151, v150, vcc
	v_sqrt_f32_e32 v151, v150
	s_nop 0
	v_add_u32_e32 v152, -1, v151
	v_fma_f32 v153, -v152, v151, v150
	v_cmp_ge_f32_e64 s[2:3], 0, v153
	v_add_u32_e32 v153, 1, v151
	s_nop 0
	v_cndmask_b32_e64 v152, v151, v152, s[2:3]
	v_fma_f32 v151, -v153, v151, v150
	v_cmp_lt_f32_e64 s[2:3], 0, v151
	s_nop 1
	v_cndmask_b32_e64 v151, v152, v153, s[2:3]
	v_mul_f32_e32 v152, 0x37800000, v151
	v_cndmask_b32_e32 v151, v151, v152, vcc
	v_cmp_class_f32_e32 vcc, v150, v196
	s_nop 1
	v_cndmask_b32_e32 v150, v151, v150, vcc
	v_div_scale_f32 v151, s[2:3], v150, v150, 1.0
	v_rcp_f32_e32 v152, v151
	s_nop 0
	v_fma_f32 v153, -v151, v152, 1.0
	v_fmac_f32_e32 v152, v153, v152
	v_div_scale_f32 v153, vcc, 1.0, v150, 1.0
	v_mul_f32_e32 v154, v153, v152
	v_fma_f32 v155, -v151, v154, v153
	v_fmac_f32_e32 v154, v155, v152
	v_fma_f32 v151, -v151, v154, v153
	v_div_fmas_f32 v151, v151, v152, v154
	v_div_fixup_f32 v150, v151, v150, 1.0
	v_mov_b32_e32 v152, 0x358637bd
	s_waitcnt vmcnt(0)
;     __device__ __forceinline__ void operator()(const Acc& acc, const Unit& u, int wr, int wc, int fr, int fq) const {
;     ...
;             for (int n = 0; n < 2; ++n) { const ssq_t* s = ssq + col0 + bj * HALF + 4 * n; rv[bj][n] = (f32x4){rms_r(s[0]), rms_r(s[1]), rms_r(s[2]), rms_r(s[3])}; }
	v_cvt_f32_u32_e32 v151, v189
	v_fmac_f32_e32 v152, 0x36800000, v151
	v_cmp_gt_f32_e32 vcc, s66, v152
	v_mul_f32_e32 v151, 0x4f800000, v152
	s_nop 0
	v_cndmask_b32_e32 v151, v152, v151, vcc
	v_sqrt_f32_e32 v152, v151
	s_nop 0
	v_add_u32_e32 v153, -1, v152
	v_fma_f32 v154, -v153, v152, v151
	v_cmp_ge_f32_e64 s[2:3], 0, v154
	v_add_u32_e32 v154, 1, v152
	s_nop 0
	v_cndmask_b32_e64 v153, v152, v153, s[2:3]
	v_fma_f32 v152, -v154, v152, v151
	v_cmp_lt_f32_e64 s[2:3], 0, v152
	s_nop 1
	v_cndmask_b32_e64 v152, v153, v154, s[2:3]
	v_mul_f32_e32 v153, 0x37800000, v152
	v_cndmask_b32_e32 v152, v152, v153, vcc
	v_cmp_class_f32_e32 vcc, v151, v196
	s_nop 1
	v_cndmask_b32_e32 v151, v152, v151, vcc
	v_div_scale_f32 v152, s[2:3], v151, v151, 1.0
	v_rcp_f32_e32 v153, v152
	s_nop 0
	v_fma_f32 v154, -v152, v153, 1.0
	v_fmac_f32_e32 v153, v154, v153
	v_div_scale_f32 v154, vcc, 1.0, v151, 1.0
	v_mul_f32_e32 v155, v154, v153
	v_fma_f32 v156, -v152, v155, v154
	v_fmac_f32_e32 v155, v156, v153
	v_fma_f32 v152, -v152, v155, v154
	v_div_fmas_f32 v152, v152, v153, v155
	v_div_fixup_f32 v151, v152, v151, 1.0
	v_mov_b32_e32 v153, 0x358637bd
	s_waitcnt vmcnt(0)
	v_cvt_f32_u32_e32 v152, v190
	v_fmac_f32_e32 v153, 0x36800000, v152
	v_cmp_gt_f32_e32 vcc, s66, v153
	v_mul_f32_e32 v152, 0x4f800000, v153
	s_nop 0
	v_cndmask_b32_e32 v152, v153, v152, vcc
	v_sqrt_f32_e32 v153, v152
	s_nop 0
	v_add_u32_e32 v154, -1, v153
	v_fma_f32 v155, -v154, v153, v152
	v_cmp_ge_f32_e64 s[2:3], 0, v155
	v_add_u32_e32 v155, 1, v153
	s_nop 0
	v_cndmask_b32_e64 v154, v153, v154, s[2:3]
	v_fma_f32 v153, -v155, v153, v152
	v_cmp_lt_f32_e64 s[2:3], 0, v153
	s_nop 1
	v_cndmask_b32_e64 v153, v154, v155, s[2:3]
	v_mul_f32_e32 v154, 0x37800000, v153
	v_cndmask_b32_e32 v153, v153, v154, vcc
	v_cmp_class_f32_e32 vcc, v152, v196
	s_nop 1
	v_cndmask_b32_e32 v152, v153, v152, vcc
	v_div_scale_f32 v153, s[2:3], v152, v152, 1.0
	v_rcp_f32_e32 v154, v153
	s_nop 0
	v_fma_f32 v155, -v153, v154, 1.0
	v_fmac_f32_e32 v154, v155, v154
	v_div_scale_f32 v155, vcc, 1.0, v152, 1.0
	v_mul_f32_e32 v156, v155, v154
	v_fma_f32 v157, -v153, v156, v155
	v_fmac_f32_e32 v156, v157, v154
	v_fma_f32 v153, -v153, v156, v155
	v_div_fmas_f32 v153, v153, v154, v156
	v_div_fixup_f32 v152, v153, v152, 1.0
	v_mov_b32_e32 v154, 0x358637bd
	s_waitcnt vmcnt(0)
	v_cvt_f32_u32_e32 v153, v191
	v_fmac_f32_e32 v154, 0x36800000, v153
	v_cmp_gt_f32_e32 vcc, s66, v154
	v_mul_f32_e32 v153, 0x4f800000, v154
	s_nop 0
	v_cndmask_b32_e32 v153, v154, v153, vcc
	v_sqrt_f32_e32 v154, v153
	s_nop 0
	v_add_u32_e32 v155, -1, v154
	v_fma_f32 v156, -v155, v154, v153
	v_cmp_ge_f32_e64 s[2:3], 0, v156
	v_add_u32_e32 v156, 1, v154
	s_nop 0
	v_cndmask_b32_e64 v155, v154, v155, s[2:3]
	v_fma_f32 v154, -v156, v154, v153
	v_cmp_lt_f32_e64 s[2:3], 0, v154
	s_nop 1
	v_cndmask_b32_e64 v154, v155, v156, s[2:3]
	v_mul_f32_e32 v155, 0x37800000, v154
	v_cndmask_b32_e32 v154, v154, v155, vcc
	v_cmp_class_f32_e32 vcc, v153, v196
	s_nop 1
	v_cndmask_b32_e32 v153, v154, v153, vcc
	v_div_scale_f32 v154, s[2:3], v153, v153, 1.0
	v_rcp_f32_e32 v155, v154
	s_nop 0
	v_fma_f32 v156, -v154, v155, 1.0
	v_fmac_f32_e32 v155, v156, v155
	v_div_scale_f32 v156, vcc, 1.0, v153, 1.0
	v_mul_f32_e32 v157, v156, v155
	v_fma_f32 v158, -v154, v157, v156
	v_fmac_f32_e32 v157, v158, v155
	v_fma_f32 v154, -v154, v157, v156
	v_div_fmas_f32 v154, v154, v155, v157
	v_div_fixup_f32 v153, v154, v153, 1.0
	v_mov_b32_e32 v155, 0x358637bd
	s_waitcnt vmcnt(0)
	v_cvt_f32_u32_e32 v154, v192
	v_fmac_f32_e32 v155, 0x36800000, v154
	v_cmp_gt_f32_e32 vcc, s66, v155
	v_mul_f32_e32 v154, 0x4f800000, v155
	s_nop 0
	v_cndmask_b32_e32 v154, v155, v154, vcc
	v_sqrt_f32_e32 v155, v154
	s_nop 0
	v_add_u32_e32 v156, -1, v155
	v_fma_f32 v157, -v156, v155, v154
	v_cmp_ge_f32_e64 s[2:3], 0, v157
	v_add_u32_e32 v157, 1, v155
	s_nop 0
	v_cndmask_b32_e64 v156, v155, v156, s[2:3]
	v_fma_f32 v155, -v157, v155, v154
	v_cmp_lt_f32_e64 s[2:3], 0, v155
	s_nop 1
	v_cndmask_b32_e64 v155, v156, v157, s[2:3]
	v_mul_f32_e32 v156, 0x37800000, v155
	v_cndmask_b32_e32 v155, v155, v156, vcc
	v_cmp_class_f32_e32 vcc, v154, v196
	s_nop 1
	v_cndmask_b32_e32 v154, v155, v154, vcc
	v_div_scale_f32 v155, s[2:3], v154, v154, 1.0
	v_rcp_f32_e32 v156, v155
	s_nop 0
	v_fma_f32 v157, -v155, v156, 1.0
	v_fmac_f32_e32 v156, v157, v156
	v_div_scale_f32 v157, vcc, 1.0, v154, 1.0
	v_mul_f32_e32 v158, v157, v156
	v_fma_f32 v159, -v155, v158, v157
	v_fmac_f32_e32 v158, v159, v156
	v_fma_f32 v155, -v155, v158, v157
	v_div_fmas_f32 v155, v155, v156, v158
	v_div_fixup_f32 v154, v155, v154, 1.0
	v_mov_b32_e32 v156, 0x358637bd
	s_waitcnt vmcnt(0)
	v_cvt_f32_u32_e32 v155, v193
	v_fmac_f32_e32 v156, 0x36800000, v155
	v_cmp_gt_f32_e32 vcc, s66, v156
	v_mul_f32_e32 v155, 0x4f800000, v156
	s_nop 0
	v_cndmask_b32_e32 v155, v156, v155, vcc
	v_sqrt_f32_e32 v156, v155
	s_nop 0
	v_add_u32_e32 v157, -1, v156
	v_fma_f32 v158, -v157, v156, v155
	v_cmp_ge_f32_e64 s[2:3], 0, v158
	v_add_u32_e32 v158, 1, v156
	s_nop 0
	v_cndmask_b32_e64 v157, v156, v157, s[2:3]
	v_fma_f32 v156, -v158, v156, v155
	v_cmp_lt_f32_e64 s[2:3], 0, v156
	s_nop 1
	v_cndmask_b32_e64 v156, v157, v158, s[2:3]
	v_mul_f32_e32 v157, 0x37800000, v156
	v_cndmask_b32_e32 v156, v156, v157, vcc
	v_cmp_class_f32_e32 vcc, v155, v196
	s_nop 1
	v_cndmask_b32_e32 v155, v156, v155, vcc
	v_div_scale_f32 v156, s[2:3], v155, v155, 1.0
	v_rcp_f32_e32 v157, v156
	s_nop 0
	v_fma_f32 v158, -v156, v157, 1.0
	v_fmac_f32_e32 v157, v158, v157
	v_div_scale_f32 v158, vcc, 1.0, v155, 1.0
	v_mul_f32_e32 v159, v158, v157
	v_fma_f32 v160, -v156, v159, v158
	v_fmac_f32_e32 v159, v160, v157
	v_fma_f32 v156, -v156, v159, v158
	v_div_fmas_f32 v156, v156, v157, v159
	v_div_fixup_f32 v155, v156, v155, 1.0
	global_load_dword v156, v[146:147], off offset:536
	v_mov_b32_e32 v157, 0x358637bd
	global_load_dword v146, v[146:147], off offset:540
	v_mov_b32_e32 v147, 0x358637bd
	s_waitcnt vmcnt(1)
; __device__ __forceinline__ unsigned cvt_pk_bf16(float lo, float hi) { unsigned r; asm("v_cvt_pk_bf16_f32 %0, %1, %2" : "=v"(r) : "v"(lo), "v"(hi)); return r; }
;     __device__ __forceinline__ void operator()(const Acc& acc, const Unit& u, int wr, int wc, int fr, int fq) const {
;     ...
;             for (int n = 0; n < 2; ++n) { const ssq_t* s = ssq + col0 + bj * HALF + 4 * n; rv[bj][n] = (f32x4){rms_r(s[0]), rms_r(s[1]), rms_r(s[2]), rms_r(s[3])}; }
;         float brv[8];
; #pragma unroll
;         for (int q = 0; q < 8; ++q) brv[q] = bias[row0 + (q >> 2) * HALF + (q & 3) * 16];
; #pragma unroll
;         for (int ai = 0; ai < 2; ++ai)
; #pragma unroll
;             for (int m = 0; m < 4; ++m) {
;                 const int row = row0 + ai * HALF + m * 16;
;                 const float br = brv[ai * 4 + m];
;                 bf16_t* rowp = O + (size_t)row * NTOK + col0;
; #pragma unroll
;                 for (int bj = 0; bj < 2; ++bj) {
;                     const f32x4 v0 = acc[ai][bj][m][0] * rv[bj][0] + br, v1 = acc[ai][bj][m][1] * rv[bj][1] + br;
;                     u32x4 w; w.x = cvt_pk_bf16(v0[0], v0[1]); w.y = cvt_pk_bf16(v0[2], v0[3]); w.z = cvt_pk_bf16(v1[0], v1[1]); w.w = cvt_pk_bf16(v1[2], v1[3]);
;                     *(u32x4*)(rowp + bj * HALF) = w;
;                 }
	v_cvt_f32_u32_e32 v156, v156
	s_waitcnt vmcnt(0)
	v_cvt_f32_u32_e32 v146, v146
	v_fmac_f32_e32 v157, 0x36800000, v156
	v_cmp_gt_f32_e32 vcc, s66, v157
	v_mul_f32_e32 v156, 0x4f800000, v157
	v_fmac_f32_e32 v147, 0x36800000, v146
	v_cndmask_b32_e32 v156, v157, v156, vcc
	v_sqrt_f32_e32 v157, v156
	v_mul_f32_e32 v146, 0x4f800000, v147
	v_add_u32_e32 v158, -1, v157
	v_fma_f32 v159, -v158, v157, v156
	v_cmp_ge_f32_e64 s[2:3], 0, v159
	v_add_u32_e32 v159, 1, v157
	s_nop 0
	v_cndmask_b32_e64 v158, v157, v158, s[2:3]
	v_fma_f32 v157, -v159, v157, v156
	v_cmp_lt_f32_e64 s[2:3], 0, v157
	s_nop 1
	v_cndmask_b32_e64 v157, v158, v159, s[2:3]
	v_mul_f32_e32 v158, 0x37800000, v157
	v_cndmask_b32_e32 v157, v157, v158, vcc
	v_cmp_class_f32_e32 vcc, v156, v196
	s_nop 1
	v_cndmask_b32_e32 v156, v157, v156, vcc
	v_div_scale_f32 v157, s[2:3], v156, v156, 1.0
	v_rcp_f32_e32 v158, v157
	s_nop 0
	v_fma_f32 v159, -v157, v158, 1.0
	v_fmac_f32_e32 v158, v159, v158
	v_div_scale_f32 v159, vcc, 1.0, v156, 1.0
	v_mul_f32_e32 v160, v159, v158
	v_fma_f32 v162, -v157, v160, v159
	v_fmac_f32_e32 v160, v162, v158
	v_fma_f32 v157, -v157, v160, v159
	v_div_fmas_f32 v157, v157, v158, v160
	v_cmp_gt_f32_e32 vcc, s66, v147
	v_div_fixup_f32 v156, v157, v156, 1.0
	s_nop 0
	v_cndmask_b32_e32 v146, v147, v146, vcc
	v_sqrt_f32_e32 v147, v146
	s_nop 0
	v_add_u32_e32 v157, -1, v147
	v_fma_f32 v158, -v157, v147, v146
	v_cmp_ge_f32_e64 s[2:3], 0, v158
	v_add_u32_e32 v158, 1, v147
	s_nop 0
	v_cndmask_b32_e64 v157, v147, v157, s[2:3]
	v_fma_f32 v147, -v158, v147, v146
	v_cmp_lt_f32_e64 s[2:3], 0, v147
	s_nop 1
	v_cndmask_b32_e64 v147, v157, v158, s[2:3]
	v_mul_f32_e32 v157, 0x37800000, v147
	v_cndmask_b32_e32 v147, v147, v157, vcc
	v_cmp_class_f32_e32 vcc, v146, v196
	s_nop 1
	v_cndmask_b32_e32 v146, v147, v146, vcc
	v_div_scale_f32 v147, s[2:3], v146, v146, 1.0
	v_rcp_f32_e32 v157, v147
	s_nop 0
	v_fma_f32 v158, -v147, v157, 1.0
	v_fmac_f32_e32 v157, v158, v157
	v_div_scale_f32 v158, vcc, 1.0, v146, 1.0
	v_mul_f32_e32 v159, v158, v157
	v_fma_f32 v160, -v147, v159, v158
	v_fmac_f32_e32 v159, v160, v157
	v_fma_f32 v147, -v147, v159, v158
	v_lshl_add_u32 v158, s0, 8, v161
	v_div_fmas_f32 v147, v147, v157, v159
	v_ashrrev_i32_e32 v159, 31, v158
	v_div_fixup_f32 v157, v147, v146, 1.0
	v_lshl_add_u64 v[146:147], v[158:159], 2, s[12:13]
	global_load_dword v164, v[146:147], off
	global_load_dword v166, v[146:147], off offset:64
	global_load_dword v170, v[146:147], off offset:128
	global_load_dword v172, v[146:147], off offset:192
	global_load_dword v168, v[146:147], off offset:512
	global_load_dword v162, v[146:147], off offset:576
	global_load_dword v160, v[146:147], off offset:640
	s_nop 0
	global_load_dword v146, v[146:147], off offset:704
	v_lshlrev_b64 v[174:175], 14, v[158:159]
	v_lshl_add_u64 v[174:175], s[10:11], 0, v[174:175]
	v_lshl_add_u64 v[142:143], v[174:175], 0, v[178:179]
	s_mov_b64 s[0:1], 0x200000
	s_waitcnt vmcnt(7)
	v_pk_fma_f32 v[126:127], v[126:127], v[140:141], v[164:165] op_sel_hi:[1,1,0]
	v_pk_fma_f32 v[124:125], v[124:125], v[138:139], v[164:165] op_sel_hi:[1,1,0]
	v_pk_fma_f32 v[174:175], v[122:123], v[148:149], v[164:165] op_sel_hi:[1,1,0]
	v_pk_fma_f32 v[122:123], v[120:121], v[144:145], v[164:165] op_sel_hi:[1,1,0]
	v_cvt_pk_bf16_f32 v120, v124, v125
	v_cvt_pk_bf16_f32 v121, v126, v127
	v_pk_fma_f32 v[116:117], v[116:117], v[150:151], v[164:165] op_sel_hi:[1,1,0]
	v_cvt_pk_bf16_f32 v122, v122, v123
	v_cvt_pk_bf16_f32 v123, v174, v175
	global_store_dwordx4 v[142:143], v[120:123], off sc0 sc1
	v_pk_fma_f32 v[118:119], v[118:119], v[152:153], v[164:165] op_sel_hi:[1,1,0]
	s_waitcnt vmcnt(7)
	v_pk_fma_f32 v[110:111], v[110:111], v[140:141], v[166:167] op_sel_hi:[1,1,0]
	v_pk_fma_f32 v[120:121], v[114:115], v[156:157], v[164:165] op_sel_hi:[1,1,0]
	v_pk_fma_f32 v[114:115], v[112:113], v[154:155], v[164:165] op_sel_hi:[1,1,0]
	v_cvt_pk_bf16_f32 v112, v116, v117
	v_cvt_pk_bf16_f32 v113, v118, v119
	v_pk_fma_f32 v[108:109], v[108:109], v[138:139], v[166:167] op_sel_hi:[1,1,0]
	v_cvt_pk_bf16_f32 v114, v114, v115
	v_cvt_pk_bf16_f32 v115, v120, v121
	global_store_dwordx4 v[142:143], v[112:115], off offset:256 sc0 sc1
	v_pk_fma_f32 v[100:101], v[100:101], v[150:151], v[166:167] op_sel_hi:[1,1,0]
	v_pk_fma_f32 v[102:103], v[102:103], v[152:153], v[166:167] op_sel_hi:[1,1,0]
	v_or_b32_e32 v112, 16, v158
	v_ashrrev_i32_e32 v113, 31, v112
	v_lshlrev_b64 v[112:113], 14, v[112:113]
	v_lshl_add_u64 v[112:113], s[10:11], 0, v[112:113]
	v_lshl_add_u64 v[112:113], v[112:113], 0, v[178:179]
	v_pk_fma_f32 v[114:115], v[106:107], v[148:149], v[166:167] op_sel_hi:[1,1,0]
	v_pk_fma_f32 v[106:107], v[104:105], v[144:145], v[166:167] op_sel_hi:[1,1,0]
	v_cvt_pk_bf16_f32 v104, v108, v109
	v_cvt_pk_bf16_f32 v105, v110, v111
	s_waitcnt vmcnt(7)
	v_pk_fma_f32 v[94:95], v[94:95], v[140:141], v[170:171] op_sel_hi:[1,1,0]
	v_cvt_pk_bf16_f32 v106, v106, v107
	v_cvt_pk_bf16_f32 v107, v114, v115
	global_store_dwordx4 v[112:113], v[104:107], off sc0 sc1
	v_pk_fma_f32 v[92:93], v[92:93], v[138:139], v[170:171] op_sel_hi:[1,1,0]
	v_pk_fma_f32 v[84:85], v[84:85], v[150:151], v[170:171] op_sel_hi:[1,1,0]
	v_pk_fma_f32 v[104:105], v[98:99], v[156:157], v[166:167] op_sel_hi:[1,1,0]
	v_pk_fma_f32 v[98:99], v[96:97], v[154:155], v[166:167] op_sel_hi:[1,1,0]
	v_cvt_pk_bf16_f32 v96, v100, v101
	v_cvt_pk_bf16_f32 v97, v102, v103
	v_pk_fma_f32 v[86:87], v[86:87], v[152:153], v[170:171] op_sel_hi:[1,1,0]
	v_cvt_pk_bf16_f32 v98, v98, v99
	v_cvt_pk_bf16_f32 v99, v104, v105
	global_store_dwordx4 v[112:113], v[96:99], off offset:256 sc0 sc1
	s_waitcnt vmcnt(8)
; __device__ __forceinline__ unsigned cvt_pk_bf16(float lo, float hi) { unsigned r; asm("v_cvt_pk_bf16_f32 %0, %1, %2" : "=v"(r) : "v"(lo), "v"(hi)); return r; }
;     __device__ __forceinline__ void operator()(const Acc& acc, const Unit& u, int wr, int wc, int fr, int fq) const {
;     ...
; #pragma unroll
;         for (int ai = 0; ai < 2; ++ai)
; #pragma unroll
;             for (int m = 0; m < 4; ++m) {
;                 const int row = row0 + ai * HALF + m * 16;
;                 const float br = brv[ai * 4 + m];
;                 bf16_t* rowp = O + (size_t)row * NTOK + col0;
; #pragma unroll
;                 for (int bj = 0; bj < 2; ++bj) {
;                     const f32x4 v0 = acc[ai][bj][m][0] * rv[bj][0] + br, v1 = acc[ai][bj][m][1] * rv[bj][1] + br;
;                     u32x4 w; w.x = cvt_pk_bf16(v0[0], v0[1]); w.y = cvt_pk_bf16(v0[2], v0[3]); w.z = cvt_pk_bf16(v1[0], v1[1]); w.w = cvt_pk_bf16(v1[2], v1[3]);
;                     *(u32x4*)(rowp + bj * HALF) = w;
;                 }
	v_pk_fma_f32 v[78:79], v[78:79], v[140:141], v[172:173] op_sel_hi:[1,1,0]
	v_pk_fma_f32 v[76:77], v[76:77], v[138:139], v[172:173] op_sel_hi:[1,1,0]
	v_or_b32_e32 v96, 32, v158
	v_ashrrev_i32_e32 v97, 31, v96
	v_lshlrev_b64 v[96:97], 14, v[96:97]
	v_lshl_add_u64 v[96:97], s[10:11], 0, v[96:97]
	v_lshl_add_u64 v[96:97], v[96:97], 0, v[178:179]
	v_pk_fma_f32 v[98:99], v[90:91], v[148:149], v[170:171] op_sel_hi:[1,1,0]
	v_pk_fma_f32 v[90:91], v[88:89], v[144:145], v[170:171] op_sel_hi:[1,1,0]
	v_cvt_pk_bf16_f32 v88, v92, v93
	v_cvt_pk_bf16_f32 v89, v94, v95
	v_pk_fma_f32 v[70:71], v[70:71], v[152:153], v[172:173] op_sel_hi:[1,1,0]
	v_cvt_pk_bf16_f32 v90, v90, v91
	v_cvt_pk_bf16_f32 v91, v98, v99
	global_store_dwordx4 v[96:97], v[88:91], off sc0 sc1
	v_pk_fma_f32 v[68:69], v[68:69], v[150:151], v[172:173] op_sel_hi:[1,1,0]
	s_waitcnt vmcnt(8)
	v_pk_fma_f32 v[60:61], v[60:61], v[138:139], v[168:169] op_sel_hi:[1,1,0]
	v_pk_fma_f32 v[88:89], v[82:83], v[156:157], v[170:171] op_sel_hi:[1,1,0]
	v_pk_fma_f32 v[82:83], v[80:81], v[154:155], v[170:171] op_sel_hi:[1,1,0]
	v_cvt_pk_bf16_f32 v80, v84, v85
	v_cvt_pk_bf16_f32 v81, v86, v87
	v_pk_fma_f32 v[62:63], v[62:63], v[140:141], v[168:169] op_sel_hi:[1,1,0]
	v_cvt_pk_bf16_f32 v82, v82, v83
	v_cvt_pk_bf16_f32 v83, v88, v89
	global_store_dwordx4 v[96:97], v[80:83], off offset:256 sc0 sc1
	v_pk_fma_f32 v[54:55], v[54:55], v[152:153], v[168:169] op_sel_hi:[1,1,0]
	v_pk_fma_f32 v[52:53], v[52:53], v[150:151], v[168:169] op_sel_hi:[1,1,0]
	v_or_b32_e32 v80, 48, v158
	v_ashrrev_i32_e32 v81, 31, v80
	v_lshlrev_b64 v[80:81], 14, v[80:81]
	v_lshl_add_u64 v[80:81], s[10:11], 0, v[80:81]
	v_lshl_add_u64 v[80:81], v[80:81], 0, v[178:179]
	v_pk_fma_f32 v[82:83], v[74:75], v[148:149], v[172:173] op_sel_hi:[1,1,0]
	v_pk_fma_f32 v[74:75], v[72:73], v[144:145], v[172:173] op_sel_hi:[1,1,0]
	v_cvt_pk_bf16_f32 v72, v76, v77
	v_cvt_pk_bf16_f32 v73, v78, v79
	s_waitcnt vmcnt(8)
	v_pk_fma_f32 v[48:49], v[48:49], v[138:139], v[162:163] op_sel_hi:[1,1,0]
	v_cvt_pk_bf16_f32 v74, v74, v75
	v_cvt_pk_bf16_f32 v75, v82, v83
	global_store_dwordx4 v[80:81], v[72:75], off sc0 sc1
	v_pk_fma_f32 v[38:39], v[38:39], v[152:153], v[162:163] op_sel_hi:[1,1,0]
	v_pk_fma_f32 v[36:37], v[36:37], v[150:151], v[162:163] op_sel_hi:[1,1,0]
	v_pk_fma_f32 v[72:73], v[66:67], v[156:157], v[172:173] op_sel_hi:[1,1,0]
	v_pk_fma_f32 v[66:67], v[64:65], v[154:155], v[172:173] op_sel_hi:[1,1,0]
	v_cvt_pk_bf16_f32 v64, v68, v69
	v_cvt_pk_bf16_f32 v65, v70, v71
	s_waitcnt vmcnt(8)
	v_pk_fma_f32 v[32:33], v[32:33], v[138:139], v[160:161] op_sel_hi:[1,1,0]
	v_cvt_pk_bf16_f32 v66, v66, v67
	v_cvt_pk_bf16_f32 v67, v72, v73
	global_store_dwordx4 v[80:81], v[64:67], off offset:256 sc0 sc1
	v_pk_fma_f32 v[22:23], v[22:23], v[152:153], v[160:161] op_sel_hi:[1,1,0]
	v_pk_fma_f32 v[20:21], v[20:21], v[150:151], v[160:161] op_sel_hi:[1,1,0]
	v_lshl_add_u64 v[64:65], v[142:143], 0, s[0:1]
	s_mov_b32 s0, 0x200000
	v_pk_fma_f32 v[66:67], v[58:59], v[148:149], v[168:169] op_sel_hi:[1,1,0]
	v_pk_fma_f32 v[58:59], v[56:57], v[144:145], v[168:169] op_sel_hi:[1,1,0]
	v_cvt_pk_bf16_f32 v56, v60, v61
	v_add_co_u32_e32 v60, vcc, s0, v142
	v_cvt_pk_bf16_f32 v57, v62, v63
	v_cvt_pk_bf16_f32 v58, v58, v59
	v_cvt_pk_bf16_f32 v59, v66, v67
	s_mov_b64 s[0:1], 0x240000
	s_nop 0
	v_addc_co_u32_e32 v61, vcc, 0, v143, vcc
	global_store_dwordx4 v[60:61], v[56:59], off sc0 sc1
	s_waitcnt vmcnt(9)
	v_pk_fma_f32 v[16:17], v[16:17], v[138:139], v[146:147] op_sel_hi:[1,1,0]
	v_pk_fma_f32 v[6:7], v[6:7], v[152:153], v[146:147] op_sel_hi:[1,1,0]
	v_pk_fma_f32 v[56:57], v[46:47], v[156:157], v[168:169] op_sel_hi:[1,1,0]
	v_pk_fma_f32 v[46:47], v[44:45], v[154:155], v[168:169] op_sel_hi:[1,1,0]
	v_cvt_pk_bf16_f32 v44, v52, v53
	v_cvt_pk_bf16_f32 v45, v54, v55
	v_pk_fma_f32 v[4:5], v[4:5], v[150:151], v[146:147] op_sel_hi:[1,1,0]
	v_cvt_pk_bf16_f32 v46, v46, v47
	v_cvt_pk_bf16_f32 v47, v56, v57
	global_store_dwordx4 v[64:65], v[44:47], off offset:256 sc0 sc1
	s_nop 1
	v_lshl_add_u64 v[44:45], v[142:143], 0, s[0:1]
	v_pk_fma_f32 v[46:47], v[50:51], v[140:141], v[162:163] op_sel_hi:[1,1,0]
	s_mov_b32 s0, 0x240000
	v_pk_fma_f32 v[50:51], v[42:43], v[148:149], v[162:163] op_sel_hi:[1,1,0]
	v_pk_fma_f32 v[42:43], v[40:41], v[144:145], v[162:163] op_sel_hi:[1,1,0]
	v_cvt_pk_bf16_f32 v41, v46, v47
	v_add_co_u32_e32 v46, vcc, s0, v142
	v_cvt_pk_bf16_f32 v40, v48, v49
	v_cvt_pk_bf16_f32 v42, v42, v43
	v_cvt_pk_bf16_f32 v43, v50, v51
	s_mov_b64 s[0:1], 0x280000
	s_nop 0
	v_addc_co_u32_e32 v47, vcc, 0, v143, vcc
	global_store_dwordx4 v[46:47], v[40:43], off sc0 sc1
	s_nop 1
	v_pk_fma_f32 v[40:41], v[30:31], v[156:157], v[162:163] op_sel_hi:[1,1,0]
	v_pk_fma_f32 v[30:31], v[28:29], v[154:155], v[162:163] op_sel_hi:[1,1,0]
	v_cvt_pk_bf16_f32 v28, v36, v37
	v_cvt_pk_bf16_f32 v29, v38, v39
	s_nop 0
	v_cvt_pk_bf16_f32 v30, v30, v31
	v_cvt_pk_bf16_f32 v31, v40, v41
	global_store_dwordx4 v[44:45], v[28:31], off offset:256 sc0 sc1
	s_nop 1
	v_lshl_add_u64 v[28:29], v[142:143], 0, s[0:1]
	v_pk_fma_f32 v[30:31], v[34:35], v[140:141], v[160:161] op_sel_hi:[1,1,0]
	s_mov_b32 s0, 0x280000
	v_pk_fma_f32 v[34:35], v[26:27], v[148:149], v[160:161] op_sel_hi:[1,1,0]
	v_pk_fma_f32 v[26:27], v[24:25], v[144:145], v[160:161] op_sel_hi:[1,1,0]
	v_cvt_pk_bf16_f32 v25, v30, v31
	v_add_co_u32_e32 v30, vcc, s0, v142
	v_cvt_pk_bf16_f32 v24, v32, v33
	v_cvt_pk_bf16_f32 v26, v26, v27
	v_cvt_pk_bf16_f32 v27, v34, v35
	s_mov_b64 s[0:1], 0x2c0000
	s_nop 0
	v_addc_co_u32_e32 v31, vcc, 0, v143, vcc
	global_store_dwordx4 v[30:31], v[24:27], off sc0 sc1
	s_nop 1
	v_pk_fma_f32 v[24:25], v[14:15], v[156:157], v[160:161] op_sel_hi:[1,1,0]
	v_pk_fma_f32 v[14:15], v[12:13], v[154:155], v[160:161] op_sel_hi:[1,1,0]
	v_cvt_pk_bf16_f32 v12, v20, v21
	v_cvt_pk_bf16_f32 v13, v22, v23
	s_nop 0
	v_cvt_pk_bf16_f32 v14, v14, v15
	v_cvt_pk_bf16_f32 v15, v24, v25
	global_store_dwordx4 v[28:29], v[12:15], off offset:256 sc0 sc1
	s_nop 1
	v_lshl_add_u64 v[12:13], v[142:143], 0, s[0:1]
	v_pk_fma_f32 v[14:15], v[18:19], v[140:141], v[146:147] op_sel_hi:[1,1,0]
	s_mov_b32 s0, 0x2c0000
	v_pk_fma_f32 v[18:19], v[10:11], v[148:149], v[146:147] op_sel_hi:[1,1,0]
	v_pk_fma_f32 v[10:11], v[8:9], v[144:145], v[146:147] op_sel_hi:[1,1,0]
	v_cvt_pk_bf16_f32 v9, v14, v15
	v_add_co_u32_e32 v14, vcc, s0, v142
	v_cvt_pk_bf16_f32 v8, v16, v17
	v_cvt_pk_bf16_f32 v10, v10, v11
	v_cvt_pk_bf16_f32 v11, v18, v19
	s_mov_b64 s[0:1], -1
	s_nop 0
	v_addc_co_u32_e32 v15, vcc, 0, v143, vcc
	global_store_dwordx4 v[14:15], v[8:11], off sc0 sc1
	s_andn2_b64 vcc, exec, s[28:29]
	s_nop 0
	v_pk_fma_f32 v[8:9], v[2:3], v[156:157], v[146:147] op_sel_hi:[1,1,0]
	v_pk_fma_f32 v[2:3], v[0:1], v[154:155], v[146:147] op_sel_hi:[1,1,0]
	v_cvt_pk_bf16_f32 v0, v4, v5
	v_cvt_pk_bf16_f32 v1, v6, v7
	s_nop 0
	v_cvt_pk_bf16_f32 v2, v2, v3
	v_cvt_pk_bf16_f32 v3, v8, v9
	global_store_dwordx4 v[12:13], v[0:3], off offset:256 sc0 sc1
	s_cbranch_vccnz .LBB0_356
	s_andn2_b64 vcc, exec, s[8:9]
	s_cbranch_vccnz .LBB0_355
	s_barrier
	s_branch .LBB0_355
